# v22: v18 + dil run start: first item's query rows requested together with the key blocks
# baseline (speedup 1.0000x reference)
; #define LAS __attribute__((address_space(3)))
; __device__ __forceinline__ float bf2f(unsigned h) { return __uint_as_float(h << 16); }
; __device__ __forceinline__ unsigned pk2(float lo, float hi) { return pg8::cvt_pk_bf16(lo, hi); }
; __device__ __forceinline__ void da_blk_stage(const Ctx& X, const f32x4 g0, const f32x4 g1, int kb, const DaBlk& R) {
;     ...
;     for (int p = 0; p < 2; ++p) { const int row = slot * 64 + (X.tid >> 4) + 32 * p, c8 = X.tid & 15; const v4u kw = R.kw[p], vw = R.vw[p];
;         float f[8]; f[0] = bf2f(kw.x & 0xffffu); f[1] = bf2f(kw.x >> 16); f[2] = bf2f(kw.y & 0xffffu); f[3] = bf2f(kw.y >> 16); f[4] = bf2f(kw.z & 0xffffu); f[5] = bf2f(kw.z >> 16); f[6] = bf2f(kw.w & 0xffffu); f[7] = bf2f(kw.w >> 16);
;         float s = 0.f;
; #pragma unroll
;         for (int e = 0; e < 8; ++e) s += f[e] * f[e];
;         s += __shfl_xor(s, 1); s += __shfl_xor(s, 2); s += __shfl_xor(s, 4); s += __shfl_xor(s, 8);
;         const float sc = __builtin_amdgcn_rsqf(s * (1.0f / 128.0f) + EPS);
;         v4u o; o.x = pk2(f[0] * sc * g0.x, f[1] * sc * g0.y); o.y = pk2(f[2] * sc * g0.z, f[3] * sc * g0.w); o.z = pk2(f[4] * sc * g1.x, f[5] * sc * g1.y); o.w = pk2(f[6] * sc * g1.z, f[7] * sc * g1.w);
;         *(LAS v4u*)(KN + row * 272 + c8 * 16) = o;
;         LAS unsigned short* d = (LAS unsigned short*)(VT + (8 * c8) * 400 + (row ^ (8 * (c8 & 7))) * 2);
;         d[0] = (unsigned short)vw.x; d[200] = (unsigned short)(vw.x >> 16); d[400] = (unsigned short)vw.y; d[600] = (unsigned short)(vw.y >> 16);
;         d[800] = (unsigned short)vw.z; d[1000] = (unsigned short)(vw.z >> 16); d[1200] = (unsigned short)vw.w; d[1400] = (unsigned short)(vw.w >> 16); }
; __device__ __forceinline__ void da_q_load(const Ctx& X, const bf16* H, const DaRun& I, int nb, v4u (&qw)[2][4]) {
;     const int fr = X.lane & 15, fq = X.lane >> 4, qh = X.wave & 1;
; #pragma unroll
;     for (int u = 0; u < 2; ++u) { const size_t m = (size_t)I.b * SEQ + (size_t)(I.rho * (SEQ / I.dil) + 64 * nb + 32 * qh + 16 * u + fr);
; #pragma unroll
;         for (int ks = 0; ks < 4; ++ks) qw[u][ks] = *(const v4u*)hptr(H, m, I.qcol + 32 * ks + 8 * fq); }
.LBB0_268:
	s_or_b64 exec, exec, s[22:23]
	s_and_b64 s[98:99], s[4:5], exec
	s_cselect_b32 s32, 11, 9
	s_and_b64 s[98:99], s[16:17], exec
	s_cselect_b32 s32, 13, s32
	s_lshl_b32 s79, s70, s32
	s_mov_b32 s100, s12
	s_ashr_i32 s101, s12, 31
	s_lshl_b64 s[100:101], s[100:101], 21
	s_add_u32 s100, s36, s100
	s_addc_u32 s101, s37, s101
	s_lshr_b32 s98, s51, 7
	s_mov_b32 s99, s35
	s_lshl_b64 s[98:99], s[98:99], 22
	v_lshl_or_b32 v236, s15, 6, v133
	v_add_u32_e32 v236, s79, v236
	v_ashrrev_i32_e32 v237, 31, v236
	v_lshlrev_b64 v[232:233], 8, v[236:237]
	v_add_u32_e32 v236, 16, v236
	v_ashrrev_i32_e32 v237, 31, v236
	v_lshlrev_b64 v[234:235], 8, v[236:237]
	v_lshl_add_u64 v[232:233], s[100:101], 0, v[232:233]
	v_lshl_add_u64 v[234:235], s[100:101], 0, v[234:235]
	v_lshl_add_u64 v[232:233], v[232:233], 0, s[98:99]
	v_lshl_add_u64 v[234:235], v[234:235], 0, s[98:99]
	v_mov_b32_e32 v238, v118
	v_mov_b32_e32 v239, 0
	v_lshl_add_u64 v[232:233], v[232:233], 0, v[238:239]
	v_lshl_add_u64 v[234:235], v[234:235], 0, v[238:239]
	global_load_dwordx4 v[200:203], v[232:233], off
	global_load_dwordx4 v[204:207], v[232:233], off offset:64
	global_load_dwordx4 v[208:211], v[232:233], off offset:128
	global_load_dwordx4 v[212:215], v[232:233], off offset:192
	global_load_dwordx4 v[216:219], v[234:235], off
	global_load_dwordx4 v[220:223], v[234:235], off offset:64
	global_load_dwordx4 v[224:227], v[234:235], off offset:128
	global_load_dwordx4 v[228:231], v[234:235], off offset:192
	s_waitcnt vmcnt(0)
	s_and_saveexec_b64 s[98:99], s[40:41]
	ds_write_b32 v111, v251
	s_or_b64 exec, exec, s[98:99]
	v_lshlrev_b32_e32 v70, 16, v54
	v_and_b32_e32 v71, 0xffff0000, v54
	v_lshlrev_b32_e32 v66, 16, v55
	v_and_b32_e32 v67, 0xffff0000, v55
	v_pk_mul_f32 v[54:55], v[70:71], v[70:71]
	v_pk_mul_f32 v[68:69], v[66:67], v[66:67]
	v_add_f32_e32 v54, v54, v55
	v_lshlrev_b32_e32 v64, 16, v56
	v_and_b32_e32 v65, 0xffff0000, v56
	v_add_f32_e32 v54, v68, v54
	v_and_b32_e32 v58, 64, v195
	v_lshlrev_b32_e32 v60, 16, v57
	v_and_b32_e32 v61, 0xffff0000, v57
	v_pk_mul_f32 v[56:57], v[64:65], v[64:65]
	v_add_f32_e32 v54, v69, v54
	v_xor_b32_e32 v59, 1, v195
	v_add_u32_e32 v58, 64, v58
	v_add_f32_e32 v54, v56, v54
	v_cmp_lt_i32_e32 vcc, v59, v58
	v_pk_mul_f32 v[62:63], v[60:61], v[60:61]
	v_add_f32_e32 v54, v57, v54
	v_cndmask_b32_e32 v59, v195, v59, vcc
	v_add_f32_e32 v54, v62, v54
	v_lshlrev_b32_e32 v156, 2, v59
	v_add_f32_e32 v54, v63, v54
	v_xor_b32_e32 v59, 2, v195
	v_cmp_lt_i32_e32 vcc, v59, v58
	s_lshr_b32 s52, s52, 5
	s_and_b64 s[0:1], s[0:1], exec
	v_cndmask_b32_e32 v59, v195, v59, vcc
	v_lshlrev_b32_e32 v157, 2, v59
	s_waitcnt lgkmcnt(0)
	s_nop 1
	v_add_f32_dpp v54, v54, v54 quad_perm:[1,0,3,2] row_mask:0xf bank_mask:0xf
	v_xor_b32_e32 v59, 4, v195
	v_cmp_lt_i32_e32 vcc, v59, v58
	s_cselect_b32 s22, 1, -1
	s_and_b64 s[0:1], s[4:5], exec
	v_cndmask_b32_e32 v59, v195, v59, vcc
	v_lshlrev_b32_e32 v158, 2, v59
	s_waitcnt lgkmcnt(0)
	s_nop 1
	v_add_f32_dpp v54, v54, v54 quad_perm:[2,3,0,1] row_mask:0xf bank_mask:0xf
	v_xor_b32_e32 v59, 8, v195
	v_cmp_lt_i32_e32 vcc, v59, v58
	s_movk_i32 s0, 0x800
	s_cselect_b32 s13, s0, 0x200
	v_cndmask_b32_e32 v59, v195, v59, vcc
	v_lshlrev_b32_e32 v161, 2, v59
	s_waitcnt lgkmcnt(0)
	s_nop 1
	v_add_f32_dpp v54, v54, v54 row_half_mirror row_mask:0xf bank_mask:0xf
	s_and_b64 s[0:1], s[16:17], exec
	s_mul_hi_i32 s0, s55, 0x55555556
	s_cselect_b32 s23, 0x2000, s13
	s_lshr_b32 s1, s0, 31
	s_waitcnt lgkmcnt(0)
	s_nop 1
	v_add_f32_dpp v54, v54, v54 row_mirror row_mask:0xf bank_mask:0xf
	v_fmamk_f32 v54, v54, 0x3c000000, v1
	s_add_i32 s0, s0, s1
	v_rsq_f32_e32 v62, v54
	s_mul_i32 s0, s0, 3
	s_sub_i32 s0, s55, s0
	s_lshl_b32 s1, s0, 6
	s_add_i32 s13, s1, 0xc0
	v_pk_mul_f32 v[54:55], v[62:63], v[70:71] op_sel_hi:[0,1]
	v_pk_mul_f32 v[56:57], v[62:63], v[66:67] op_sel_hi:[0,1]
	s_cmp_lt_i32 s0, 0
	v_pk_mul_f32 v[54:55], v[2:3], v[54:55]
	v_pk_mul_f32 v[56:57], v[4:5], v[56:57]
	s_cselect_b32 s0, s13, s1
	v_cvt_pk_bf16_f32 v54, v54, v55
	v_cvt_pk_bf16_f32 v55, v56, v57
	v_pk_mul_f32 v[56:57], v[62:63], v[64:65] op_sel_hi:[0,1]
	v_pk_mul_f32 v[60:61], v[62:63], v[60:61] op_sel_hi:[0,1]
	v_add_u32_e32 v59, s0, v129
	v_pk_mul_f32 v[56:57], v[6:7], v[56:57]
	v_pk_mul_f32 v[60:61], v[8:9], v[60:61]
	v_cvt_pk_bf16_f32 v56, v56, v57
	v_cvt_pk_bf16_f32 v57, v60, v61
	v_mad_u64_u32 v[60:61], s[0:1], v59, s27, v[112:113]
	v_lshlrev_b32_e32 v64, 16, v46
	v_and_b32_e32 v65, 0xffff0000, v46
	ds_write_b128 v60, v[54:57]
	v_xor_b32_e32 v54, v59, v132
	v_lshlrev_b32_e32 v56, 16, v47
	v_and_b32_e32 v57, 0xffff0000, v47
	v_pk_mul_f32 v[46:47], v[64:65], v[64:65]
	v_lshl_add_u32 v54, v54, 1, v131
	v_pk_mul_f32 v[62:63], v[56:57], v[56:57]
	v_add_f32_e32 v46, v46, v47
	ds_write_b16 v54, v50 offset:52224
	ds_write_b16_d16_hi v54, v50 offset:52624
	ds_write_b16 v54, v51 offset:53024
	ds_write_b16_d16_hi v54, v51 offset:53424
	ds_write_b16 v54, v52 offset:53824
	ds_write_b16_d16_hi v54, v52 offset:54224
	ds_write_b16 v54, v53 offset:54624
	ds_write_b16_d16_hi v54, v53 offset:55024
	v_lshlrev_b32_e32 v54, 16, v48
	v_and_b32_e32 v55, 0xffff0000, v48
	v_add_f32_e32 v46, v62, v46
	v_lshlrev_b32_e32 v50, 16, v49
	v_and_b32_e32 v51, 0xffff0000, v49
	v_pk_mul_f32 v[48:49], v[54:55], v[54:55]
	v_add_f32_e32 v46, v63, v46
	v_add_f32_e32 v46, v48, v46
	v_pk_mul_f32 v[52:53], v[50:51], v[50:51]
	v_add_f32_e32 v46, v49, v46
	v_add_f32_e32 v46, v52, v46
	v_add_f32_e32 v46, v53, v46
	v_add_u32_e32 v59, 32, v59
	s_mul_hi_i32 s0, s15, 0x55555556
	s_lshr_b32 s1, s0, 31
	s_add_i32 s0, s0, s1
	s_waitcnt lgkmcnt(0)
; #define LAS __attribute__((address_space(3)))
; __device__ __forceinline__ float bf2f(unsigned h) { return __uint_as_float(h << 16); }
; __device__ __forceinline__ unsigned pk2(float lo, float hi) { return pg8::cvt_pk_bf16(lo, hi); }
; __device__ __forceinline__ void da_blk_stage(const Ctx& X, const f32x4 g0, const f32x4 g1, int kb, const DaBlk& R) {
;     ...
;     for (int p = 0; p < 2; ++p) { const int row = slot * 64 + (X.tid >> 4) + 32 * p, c8 = X.tid & 15; const v4u kw = R.kw[p], vw = R.vw[p];
;         float f[8]; f[0] = bf2f(kw.x & 0xffffu); f[1] = bf2f(kw.x >> 16); f[2] = bf2f(kw.y & 0xffffu); f[3] = bf2f(kw.y >> 16); f[4] = bf2f(kw.z & 0xffffu); f[5] = bf2f(kw.z >> 16); f[6] = bf2f(kw.w & 0xffffu); f[7] = bf2f(kw.w >> 16);
;         float s = 0.f;
; #pragma unroll
;         for (int e = 0; e < 8; ++e) s += f[e] * f[e];
;         s += __shfl_xor(s, 1); s += __shfl_xor(s, 2); s += __shfl_xor(s, 4); s += __shfl_xor(s, 8);
;         const float sc = __builtin_amdgcn_rsqf(s * (1.0f / 128.0f) + EPS);
;         v4u o; o.x = pk2(f[0] * sc * g0.x, f[1] * sc * g0.y); o.y = pk2(f[2] * sc * g0.z, f[3] * sc * g0.w); o.z = pk2(f[4] * sc * g1.x, f[5] * sc * g1.y); o.w = pk2(f[6] * sc * g1.z, f[7] * sc * g1.w);
;         *(LAS v4u*)(KN + row * 272 + c8 * 16) = o;
;         LAS unsigned short* d = (LAS unsigned short*)(VT + (8 * c8) * 400 + (row ^ (8 * (c8 & 7))) * 2);
;         d[0] = (unsigned short)vw.x; d[200] = (unsigned short)(vw.x >> 16); d[400] = (unsigned short)vw.y; d[600] = (unsigned short)(vw.y >> 16);
;         d[800] = (unsigned short)vw.z; d[1000] = (unsigned short)(vw.z >> 16); d[1200] = (unsigned short)vw.w; d[1400] = (unsigned short)(vw.w >> 16); }
	s_nop 1
	v_add_f32_dpp v46, v46, v46 quad_perm:[1,0,3,2] row_mask:0xf bank_mask:0xf
	s_mul_i32 s0, s0, 3
	s_sub_i32 s0, s15, s0
	s_lshl_b32 s1, s0, 6
	s_add_i32 s13, s1, 0xc0
	s_waitcnt lgkmcnt(0)
	s_nop 1
	v_add_f32_dpp v46, v46, v46 quad_perm:[2,3,0,1] row_mask:0xf bank_mask:0xf
	s_cmp_lt_i32 s0, 0
	s_cselect_b32 s0, s13, s1
	v_mov_b32_e32 v119, v159
	s_mov_b32 s30, 0
	s_waitcnt lgkmcnt(0)
	s_nop 1
	v_add_f32_dpp v46, v46, v46 row_half_mirror row_mask:0xf bank_mask:0xf
	s_mov_b32 s31, 4
	s_waitcnt lgkmcnt(0)
	s_nop 1
	v_add_f32_dpp v46, v46, v46 row_mirror row_mask:0xf bank_mask:0xf
	v_fmamk_f32 v46, v46, 0x3c000000, v1
	v_rsq_f32_e32 v52, v46
	s_nop 0
	v_pk_mul_f32 v[46:47], v[52:53], v[64:65] op_sel_hi:[0,1]
	v_pk_mul_f32 v[48:49], v[52:53], v[56:57] op_sel_hi:[0,1]
	v_pk_mul_f32 v[46:47], v[2:3], v[46:47]
	v_pk_mul_f32 v[48:49], v[4:5], v[48:49]
	v_cvt_pk_bf16_f32 v46, v46, v47
	v_cvt_pk_bf16_f32 v47, v48, v49
	v_pk_mul_f32 v[48:49], v[52:53], v[54:55] op_sel_hi:[0,1]
	v_pk_mul_f32 v[50:51], v[52:53], v[50:51] op_sel_hi:[0,1]
	v_pk_mul_f32 v[48:49], v[6:7], v[48:49]
	v_pk_mul_f32 v[50:51], v[8:9], v[50:51]
	v_cvt_pk_bf16_f32 v48, v48, v49
	v_cvt_pk_bf16_f32 v49, v50, v51
	v_lshlrev_b32_e32 v52, 16, v42
	v_and_b32_e32 v53, 0xffff0000, v42
	ds_write_b128 v60, v[46:49] offset:8704
	v_xor_b32_e32 v46, v59, v132
	v_lshlrev_b32_e32 v48, 16, v43
	v_and_b32_e32 v49, 0xffff0000, v43
	v_pk_mul_f32 v[42:43], v[52:53], v[52:53]
	v_lshl_add_u32 v46, v46, 1, v131
	v_pk_mul_f32 v[50:51], v[48:49], v[48:49]
	v_add_f32_e32 v42, v42, v43
	ds_write_b16 v46, v38 offset:52224
	ds_write_b16_d16_hi v46, v38 offset:52624
	ds_write_b16 v46, v39 offset:53024
	ds_write_b16_d16_hi v46, v39 offset:53424
	ds_write_b16 v46, v40 offset:53824
	ds_write_b16_d16_hi v46, v40 offset:54224
	ds_write_b16 v46, v41 offset:54624
	ds_write_b16_d16_hi v46, v41 offset:55024
	v_lshlrev_b32_e32 v40, 16, v44
	v_and_b32_e32 v41, 0xffff0000, v44
	v_add_f32_e32 v42, v50, v42
	v_lshlrev_b32_e32 v46, 16, v45
	v_and_b32_e32 v47, 0xffff0000, v45
	v_pk_mul_f32 v[44:45], v[40:41], v[40:41]
	v_add_f32_e32 v42, v51, v42
	v_add_f32_e32 v42, v44, v42
	v_pk_mul_f32 v[38:39], v[46:47], v[46:47]
	v_add_f32_e32 v42, v45, v42
	v_add_f32_e32 v38, v38, v42
	v_add_f32_e32 v38, v39, v38
	v_add_u32_e32 v54, s0, v129
	s_waitcnt lgkmcnt(0)
	s_nop 1
	v_add_f32_dpp v38, v38, v38 quad_perm:[1,0,3,2] row_mask:0xf bank_mask:0xf
	s_waitcnt lgkmcnt(0)
	s_nop 1
	v_add_f32_dpp v38, v38, v38 quad_perm:[2,3,0,1] row_mask:0xf bank_mask:0xf
	s_waitcnt lgkmcnt(0)
	s_nop 1
	v_add_f32_dpp v38, v38, v38 row_half_mirror row_mask:0xf bank_mask:0xf
	s_waitcnt lgkmcnt(0)
	s_nop 1
	v_add_f32_dpp v38, v38, v38 row_mirror row_mask:0xf bank_mask:0xf
	v_fmamk_f32 v38, v38, 0x3c000000, v1
	v_rsq_f32_e32 v42, v38
	s_nop 0
	v_pk_mul_f32 v[38:39], v[42:43], v[52:53] op_sel_hi:[0,1]
	v_pk_mul_f32 v[44:45], v[42:43], v[48:49] op_sel_hi:[0,1]
	v_pk_mul_f32 v[40:41], v[42:43], v[40:41] op_sel_hi:[0,1]
	v_pk_mul_f32 v[42:43], v[42:43], v[46:47] op_sel_hi:[0,1]
	v_pk_mul_f32 v[38:39], v[2:3], v[38:39]
	v_pk_mul_f32 v[44:45], v[4:5], v[44:45]
	v_pk_mul_f32 v[40:41], v[6:7], v[40:41]
	v_pk_mul_f32 v[42:43], v[8:9], v[42:43]
	v_cvt_pk_bf16_f32 v38, v38, v39
	v_cvt_pk_bf16_f32 v39, v44, v45
	v_cvt_pk_bf16_f32 v40, v40, v41
	v_cvt_pk_bf16_f32 v41, v42, v43
	v_mad_u64_u32 v[42:43], s[0:1], v54, s27, v[112:113]
	v_lshlrev_b32_e32 v46, 16, v30
	v_and_b32_e32 v47, 0xffff0000, v30
	ds_write_b128 v42, v[38:41]
	v_xor_b32_e32 v38, v54, v132
	v_lshlrev_b32_e32 v40, 16, v31
	v_and_b32_e32 v41, 0xffff0000, v31
	v_pk_mul_f32 v[30:31], v[46:47], v[46:47]
	v_lshl_add_u32 v38, v38, 1, v131
	v_pk_mul_f32 v[44:45], v[40:41], v[40:41]
	v_add_f32_e32 v30, v30, v31
	ds_write_b16 v38, v34 offset:52224
	ds_write_b16_d16_hi v38, v34 offset:52624
	ds_write_b16 v38, v35 offset:53024
	ds_write_b16_d16_hi v38, v35 offset:53424
	ds_write_b16 v38, v36 offset:53824
	ds_write_b16_d16_hi v38, v36 offset:54224
	ds_write_b16 v38, v37 offset:54624
	ds_write_b16_d16_hi v38, v37 offset:55024
	v_lshlrev_b32_e32 v38, 16, v32
	v_and_b32_e32 v39, 0xffff0000, v32
	v_add_f32_e32 v30, v44, v30
	v_lshlrev_b32_e32 v34, 16, v33
	v_and_b32_e32 v35, 0xffff0000, v33
	v_pk_mul_f32 v[32:33], v[38:39], v[38:39]
	v_add_f32_e32 v30, v45, v30
	v_add_f32_e32 v30, v32, v30
	v_pk_mul_f32 v[36:37], v[34:35], v[34:35]
	v_add_f32_e32 v30, v33, v30
	v_add_f32_e32 v30, v36, v30
	v_add_f32_e32 v30, v37, v30
	v_add_u32_e32 v43, 32, v54
	s_mul_hi_i32 s0, s53, 0x55555556
	s_lshr_b32 s1, s0, 31
	s_add_i32 s0, s0, s1
	s_waitcnt lgkmcnt(0)
	s_nop 1
	v_add_f32_dpp v30, v30, v30 quad_perm:[1,0,3,2] row_mask:0xf bank_mask:0xf
	s_mul_i32 s0, s0, 3
	s_sub_i32 s0, s53, s0
	s_lshl_b32 s1, s0, 6
	s_add_i32 s13, s1, 0xc0
	s_waitcnt lgkmcnt(0)
	s_nop 1
	v_add_f32_dpp v30, v30, v30 quad_perm:[2,3,0,1] row_mask:0xf bank_mask:0xf
	s_cmp_lt_i32 s0, 0
	s_cselect_b32 s0, s13, s1
	s_ashr_i32 s13, s12, 31
	s_waitcnt lgkmcnt(0)
	s_nop 1
	v_add_f32_dpp v30, v30, v30 row_half_mirror row_mask:0xf bank_mask:0xf
	s_waitcnt lgkmcnt(0)
; #define LAS __attribute__((address_space(3)))
; __device__ __forceinline__ float bf2f(unsigned h) { return __uint_as_float(h << 16); }
; __device__ __forceinline__ unsigned pk2(float lo, float hi) { return pg8::cvt_pk_bf16(lo, hi); }
; __device__ __forceinline__ void da_blk_stage(const Ctx& X, const f32x4 g0, const f32x4 g1, int kb, const DaBlk& R) {
;     ...
;     for (int p = 0; p < 2; ++p) { const int row = slot * 64 + (X.tid >> 4) + 32 * p, c8 = X.tid & 15; const v4u kw = R.kw[p], vw = R.vw[p];
;         float f[8]; f[0] = bf2f(kw.x & 0xffffu); f[1] = bf2f(kw.x >> 16); f[2] = bf2f(kw.y & 0xffffu); f[3] = bf2f(kw.y >> 16); f[4] = bf2f(kw.z & 0xffffu); f[5] = bf2f(kw.z >> 16); f[6] = bf2f(kw.w & 0xffffu); f[7] = bf2f(kw.w >> 16);
;         float s = 0.f;
; #pragma unroll
;         for (int e = 0; e < 8; ++e) s += f[e] * f[e];
;         s += __shfl_xor(s, 1); s += __shfl_xor(s, 2); s += __shfl_xor(s, 4); s += __shfl_xor(s, 8);
;         const float sc = __builtin_amdgcn_rsqf(s * (1.0f / 128.0f) + EPS);
;         v4u o; o.x = pk2(f[0] * sc * g0.x, f[1] * sc * g0.y); o.y = pk2(f[2] * sc * g0.z, f[3] * sc * g0.w); o.z = pk2(f[4] * sc * g1.x, f[5] * sc * g1.y); o.w = pk2(f[6] * sc * g1.z, f[7] * sc * g1.w);
;         *(LAS v4u*)(KN + row * 272 + c8 * 16) = o;
;         LAS unsigned short* d = (LAS unsigned short*)(VT + (8 * c8) * 400 + (row ^ (8 * (c8 & 7))) * 2);
;         d[0] = (unsigned short)vw.x; d[200] = (unsigned short)(vw.x >> 16); d[400] = (unsigned short)vw.y; d[600] = (unsigned short)(vw.y >> 16);
;         d[800] = (unsigned short)vw.z; d[1000] = (unsigned short)(vw.z >> 16); d[1200] = (unsigned short)vw.w; d[1400] = (unsigned short)(vw.w >> 16); }
	s_nop 1
	v_add_f32_dpp v30, v30, v30 row_mirror row_mask:0xf bank_mask:0xf
	v_fmamk_f32 v30, v30, 0x3c000000, v1
	v_rsq_f32_e32 v36, v30
	s_nop 0
	v_pk_mul_f32 v[30:31], v[36:37], v[46:47] op_sel_hi:[0,1]
	v_pk_mul_f32 v[32:33], v[36:37], v[40:41] op_sel_hi:[0,1]
	v_pk_mul_f32 v[30:31], v[2:3], v[30:31]
	v_pk_mul_f32 v[32:33], v[4:5], v[32:33]
	v_cvt_pk_bf16_f32 v30, v30, v31
	v_cvt_pk_bf16_f32 v31, v32, v33
	v_pk_mul_f32 v[32:33], v[36:37], v[38:39] op_sel_hi:[0,1]
	v_pk_mul_f32 v[34:35], v[36:37], v[34:35] op_sel_hi:[0,1]
	v_pk_mul_f32 v[32:33], v[6:7], v[32:33]
	v_pk_mul_f32 v[34:35], v[8:9], v[34:35]
	v_cvt_pk_bf16_f32 v32, v32, v33
	v_cvt_pk_bf16_f32 v33, v34, v35
	v_lshlrev_b32_e32 v36, 16, v26
	v_and_b32_e32 v37, 0xffff0000, v26
	ds_write_b128 v42, v[30:33] offset:8704
	v_xor_b32_e32 v30, v43, v132
	v_lshlrev_b32_e32 v32, 16, v27
	v_and_b32_e32 v33, 0xffff0000, v27
	v_pk_mul_f32 v[26:27], v[36:37], v[36:37]
	v_lshl_add_u32 v30, v30, 1, v131
	v_pk_mul_f32 v[34:35], v[32:33], v[32:33]
	v_add_f32_e32 v26, v26, v27
	ds_write_b16 v30, v22 offset:52224
	ds_write_b16_d16_hi v30, v22 offset:52624
	ds_write_b16 v30, v23 offset:53024
	ds_write_b16_d16_hi v30, v23 offset:53424
	ds_write_b16 v30, v24 offset:53824
	ds_write_b16_d16_hi v30, v24 offset:54224
	ds_write_b16 v30, v25 offset:54624
	ds_write_b16_d16_hi v30, v25 offset:55024
	v_lshlrev_b32_e32 v24, 16, v28
	v_and_b32_e32 v25, 0xffff0000, v28
	v_add_f32_e32 v26, v34, v26
	v_lshlrev_b32_e32 v30, 16, v29
	v_and_b32_e32 v31, 0xffff0000, v29
	v_pk_mul_f32 v[28:29], v[24:25], v[24:25]
	v_add_f32_e32 v26, v35, v26
	v_add_f32_e32 v26, v28, v26
	v_pk_mul_f32 v[22:23], v[30:31], v[30:31]
	v_add_f32_e32 v26, v29, v26
	v_add_f32_e32 v22, v22, v26
	v_add_f32_e32 v22, v23, v22
	v_add_u32_e32 v38, s0, v129
	s_and_b64 s[0:1], s[4:5], exec
	s_cselect_b32 s4, 11, 9
	s_and_b64 s[0:1], s[16:17], exec
	s_waitcnt lgkmcnt(0)
	s_nop 1
	v_add_f32_dpp v22, v22, v22 quad_perm:[1,0,3,2] row_mask:0xf bank_mask:0xf
	v_xor_b32_e32 v42, 16, v195
	v_cmp_lt_i32_e32 vcc, v42, v58
	s_waitcnt lgkmcnt(0)
	s_nop 1
	v_add_f32_dpp v22, v22, v22 quad_perm:[2,3,0,1] row_mask:0xf bank_mask:0xf
	v_cndmask_b32_e32 v42, v195, v42, vcc
	v_lshlrev_b32_e32 v166, 2, v42
	v_xor_b32_e32 v42, 32, v195
	v_cmp_lt_i32_e32 vcc, v42, v58
	s_waitcnt lgkmcnt(0)
	s_nop 1
	v_add_f32_dpp v22, v22, v22 row_half_mirror row_mask:0xf bank_mask:0xf
	v_cndmask_b32_e32 v42, v195, v42, vcc
	v_lshlrev_b32_e32 v167, 2, v42
	v_mov_b32_e32 v42, s52
	v_bfe_i32 v42, v42, 0, 8
	s_waitcnt lgkmcnt(0)
	s_nop 1
	v_add_f32_dpp v22, v22, v22 row_mirror row_mask:0xf bank_mask:0xf
	v_fmamk_f32 v22, v22, 0x3c000000, v1
	v_rsq_f32_e32 v26, v22
	v_ashrrev_i32_e32 v43, 31, v42
	v_lshlrev_b64 v[42:43], 2, v[42:43]
	v_lshl_add_u64 v[124:125], s[28:29], 0, v[42:43]
	v_pk_mul_f32 v[22:23], v[26:27], v[36:37] op_sel_hi:[0,1]
	v_pk_mul_f32 v[28:29], v[26:27], v[32:33] op_sel_hi:[0,1]
	v_pk_mul_f32 v[24:25], v[26:27], v[24:25] op_sel_hi:[0,1]
	v_pk_mul_f32 v[26:27], v[26:27], v[30:31] op_sel_hi:[0,1]
	v_pk_mul_f32 v[22:23], v[2:3], v[22:23]
	v_pk_mul_f32 v[28:29], v[4:5], v[28:29]
	v_pk_mul_f32 v[24:25], v[6:7], v[24:25]
	v_pk_mul_f32 v[26:27], v[8:9], v[26:27]
	v_cvt_pk_bf16_f32 v22, v22, v23
	v_cvt_pk_bf16_f32 v23, v28, v29
	v_cvt_pk_bf16_f32 v24, v24, v25
	v_cvt_pk_bf16_f32 v25, v26, v27
	v_mad_u64_u32 v[26:27], s[0:1], v38, s27, v[112:113]
	v_lshlrev_b32_e32 v30, 16, v10
	v_and_b32_e32 v31, 0xffff0000, v10
	ds_write_b128 v26, v[22:25]
	v_xor_b32_e32 v22, v38, v132
	v_lshlrev_b32_e32 v24, 16, v11
	v_and_b32_e32 v25, 0xffff0000, v11
	v_pk_mul_f32 v[10:11], v[30:31], v[30:31]
	v_lshl_add_u32 v22, v22, 1, v131
	v_pk_mul_f32 v[28:29], v[24:25], v[24:25]
	v_add_f32_e32 v10, v10, v11
	ds_write_b16 v22, v18 offset:52224
	ds_write_b16_d16_hi v22, v18 offset:52624
	ds_write_b16 v22, v19 offset:53024
	ds_write_b16_d16_hi v22, v19 offset:53424
	ds_write_b16 v22, v20 offset:53824
	ds_write_b16_d16_hi v22, v20 offset:54224
	ds_write_b16 v22, v21 offset:54624
	ds_write_b16_d16_hi v22, v21 offset:55024
	v_lshlrev_b32_e32 v22, 16, v12
	v_and_b32_e32 v23, 0xffff0000, v12
	v_add_f32_e32 v10, v28, v10
	v_lshlrev_b32_e32 v18, 16, v13
	v_and_b32_e32 v19, 0xffff0000, v13
	v_pk_mul_f32 v[12:13], v[22:23], v[22:23]
	v_add_f32_e32 v10, v29, v10
	v_add_f32_e32 v10, v12, v10
	v_pk_mul_f32 v[20:21], v[18:19], v[18:19]
	v_add_f32_e32 v10, v13, v10
	v_add_f32_e32 v10, v20, v10
	v_add_f32_e32 v10, v21, v10
	v_add_u32_e32 v27, 32, v38
	s_cselect_b32 s0, 13, s4
	s_lshl_b32 s53, s70, s0
	s_lshl_b64 s[4:5], s[12:13], 21
	s_waitcnt lgkmcnt(0)
; #define LAS __attribute__((address_space(3)))
; #define BAR_LDS() do { asm volatile("s_waitcnt lgkmcnt(0)" ::: "memory"); __builtin_amdgcn_s_barrier(); asm volatile("" ::: "memory"); } while (0)
; __device__ __forceinline__ unsigned pk2(float lo, float hi) { return pg8::cvt_pk_bf16(lo, hi); }
; __device__ __forceinline__ void da_blk_stage(const Ctx& X, const f32x4 g0, const f32x4 g1, int kb, const DaBlk& R) {
;     ...
;         v4u o; o.x = pk2(f[0] * sc * g0.x, f[1] * sc * g0.y); o.y = pk2(f[2] * sc * g0.z, f[3] * sc * g0.w); o.z = pk2(f[4] * sc * g1.x, f[5] * sc * g1.y); o.w = pk2(f[6] * sc * g1.z, f[7] * sc * g1.w);
;         *(LAS v4u*)(KN + row * 272 + c8 * 16) = o;
;         LAS unsigned short* d = (LAS unsigned short*)(VT + (8 * c8) * 400 + (row ^ (8 * (c8 & 7))) * 2);
;         d[0] = (unsigned short)vw.x; d[200] = (unsigned short)(vw.x >> 16); d[400] = (unsigned short)vw.y; d[600] = (unsigned short)(vw.y >> 16);
;         d[800] = (unsigned short)vw.z; d[1000] = (unsigned short)(vw.z >> 16); d[1200] = (unsigned short)vw.w; d[1400] = (unsigned short)(vw.w >> 16); }
; __device__ __forceinline__ void dil_run(const Ctx& X, bf16* H, int l, int run) {
;     ...
;     v4u qw_[2][4]; da_q_load(X, H, I, I.nb0, qw_);
;     BAR_LDS();
;     const int qh = X.wave & 1, kq = X.wave >> 1;
;     for (int i = 0; i < 4; ++i) {
;         const int nb = I.nb0 + I.dn * i; const size_t qtok = (size_t)((64 * nb + qi) * dil + rho);
	s_nop 1
	v_add_f32_dpp v10, v10, v10 quad_perm:[1,0,3,2] row_mask:0xf bank_mask:0xf
	s_add_u32 s0, s36, s4
	s_addc_u32 s1, s37, s5
	s_lshr_b32 s34, s51, 7
	s_lshl_b64 s[16:17], s[34:35], 22
	s_waitcnt lgkmcnt(0)
	s_nop 1
	v_add_f32_dpp v10, v10, v10 quad_perm:[2,3,0,1] row_mask:0xf bank_mask:0xf
	s_add_i32 s34, s51, 0x200
	s_lshr_b32 s34, s34, 7
	s_lshl_b64 s[54:55], s[34:35], 22
	s_lshl_b32 s71, s22, 1
	s_waitcnt lgkmcnt(0)
	s_nop 1
	v_add_f32_dpp v10, v10, v10 row_half_mirror row_mask:0xf bank_mask:0xf
	s_lshl_b64 s[58:59], s[12:13], 13
	v_add_u32_e32 v42, s53, v129
	v_lshl_add_u64 v[120:121], v[116:117], 0, s[54:55]
	s_waitcnt lgkmcnt(0)
	s_nop 1
	v_add_f32_dpp v10, v10, v10 row_mirror row_mask:0xf bank_mask:0xf
	v_fmamk_f32 v10, v10, 0x3c000000, v1
	v_rsq_f32_e32 v20, v10
	s_nop 0
	v_pk_mul_f32 v[10:11], v[20:21], v[30:31] op_sel_hi:[0,1]
	v_pk_mul_f32 v[12:13], v[20:21], v[24:25] op_sel_hi:[0,1]
	v_pk_mul_f32 v[10:11], v[2:3], v[10:11]
	v_pk_mul_f32 v[12:13], v[4:5], v[12:13]
	v_cvt_pk_bf16_f32 v10, v10, v11
	v_cvt_pk_bf16_f32 v11, v12, v13
	v_pk_mul_f32 v[12:13], v[20:21], v[22:23] op_sel_hi:[0,1]
	v_pk_mul_f32 v[18:19], v[20:21], v[18:19] op_sel_hi:[0,1]
	v_pk_mul_f32 v[12:13], v[6:7], v[12:13]
	v_pk_mul_f32 v[18:19], v[8:9], v[18:19]
	v_cvt_pk_bf16_f32 v12, v12, v13
	v_cvt_pk_bf16_f32 v13, v18, v19
	ds_write_b128 v26, v[10:13] offset:8704
	v_xor_b32_e32 v10, v27, v132
	v_lshl_add_u32 v10, v10, 1, v131
	ds_write_b16 v10, v14 offset:52224
	ds_write_b16_d16_hi v10, v14 offset:52624
	ds_write_b16 v10, v15 offset:53024
	ds_write_b16_d16_hi v10, v15 offset:53424
	ds_write_b16 v10, v16 offset:53824
	ds_write_b16_d16_hi v10, v16 offset:54224
	ds_write_b16 v10, v17 offset:54624
	ds_write_b16_d16_hi v10, v17 offset:55024
	v_mov_b32_e32 v10, v200
	v_mov_b32_e32 v11, v201
	v_mov_b32_e32 v12, v202
	v_mov_b32_e32 v13, v203
	v_mov_b32_e32 v14, v204
	v_mov_b32_e32 v15, v205
	v_mov_b32_e32 v16, v206
	v_mov_b32_e32 v17, v207
	v_mov_b32_e32 v18, v208
	v_mov_b32_e32 v19, v209
	v_mov_b32_e32 v20, v210
	v_mov_b32_e32 v21, v211
	v_mov_b32_e32 v22, v212
	v_mov_b32_e32 v23, v213
	v_mov_b32_e32 v24, v214
	v_mov_b32_e32 v25, v215
	v_mov_b32_e32 v26, v216
	v_mov_b32_e32 v27, v217
	v_mov_b32_e32 v28, v218
	v_mov_b32_e32 v29, v219
	v_mov_b32_e32 v30, v220
	v_mov_b32_e32 v31, v221
	v_mov_b32_e32 v32, v222
	v_mov_b32_e32 v33, v223
	v_mov_b32_e32 v34, v224
	v_mov_b32_e32 v35, v225
	v_mov_b32_e32 v36, v226
	v_mov_b32_e32 v37, v227
	v_mov_b32_e32 v38, v228
	v_mov_b32_e32 v39, v229
	v_mov_b32_e32 v40, v230
	v_mov_b32_e32 v41, v231
	s_add_i32 s15, s51, 0x400
	s_lshr_b32 s34, s15, 7
	s_ashr_i32 s15, s14, 31
	s_lshl_b64 s[56:57], s[34:35], 22
	s_add_i32 s34, s69, -1
	s_lshl_b64 s[14:15], s[14:15], 14
	s_add_u32 s12, s14, s58
	s_addc_u32 s13, s15, s59
	s_lshl_b32 s14, s51, 7
	s_and_b32 s14, s14, 0x1fc000
	s_add_u32 s14, s58, s14
	s_addc_u32 s15, s59, 0
	s_add_u32 s0, s0, s16
	s_addc_u32 s1, s1, s17
	s_add_i32 s75, s49, s50
	v_lshl_add_u64 v[126:127], s[0:1], 0, v[118:119]
	s_add_i32 s0, s75, s22
	s_lshl_b32 s0, s0, 6
	s_add_i32 s0, s0, s53
	v_or_b32_e32 v119, s0, v133
	s_add_i32 s0, s75, s71
	v_lshl_add_u32 v168, s0, 6, v42
	s_lshl_b32 s0, s48, 8
	s_lshl_b32 s1, s49, 6
	s_waitcnt lgkmcnt(0)
	s_barrier
	s_or_b32 s77, s0, s1
	s_add_i32 s0, s77, s53
	v_lshl_add_u64 v[122:123], v[116:117], 0, s[56:57]
	s_lshl_b32 s76, s22, 6
	v_or_b32_e32 v169, s77, v128
	v_add_u32_e32 v170, s0, v148
	v_add_u32_e32 v171, s77, v42
	v_add_u32_e32 v172, s77, v134
	s_add_i32 s78, s77, s21
	s_waitcnt vmcnt(0)
	s_branch .LBB0_270
